# v63 + nt stores in the prologue's cache_ckv conversion (Kc rows are consumed more than 1 ms later)
# speedup vs baseline: 1.0068x; 1.0032x over previous
.LBB0_23:
	s_ashr_i64 s[48:49], s[40:41], 12
	s_and_b32 s23, s40, 0xfff
	s_mul_i32 s40, s49, 0x1100
	s_mul_hi_u32 s41, s48, 0x1100
	s_add_i32 s41, s41, s40
	s_mul_i32 s40, s48, 0x1100
	s_add_u32 s23, s40, s23
	s_addc_u32 s40, s41, 0
	s_waitcnt vmcnt(0)
	v_cvt_pk_bf16_f32 v30, v30, v31
	v_cvt_pk_bf16_f32 v31, v32, v33
	v_cvt_pk_bf16_f32 v32, v26, v27
	s_mul_i32 s47, s40, 0x500
	v_mad_u64_u32 v[26:27], s[40:41], s23, v42, v[36:37]
	v_add_u32_e32 v27, s47, v27
	s_andn2_b64 vcc, exec, s[8:9]
	v_cvt_pk_bf16_f32 v33, v28, v29
	global_store_dwordx4 v[26:27], v[30:33], off nt
	s_cbranch_vccnz .LBB0_26
	s_ashr_i64 s[8:9], s[38:39], 12
	s_mulk_i32 s9, 0x1100
	s_mul_hi_u32 s40, s8, 0x1100
	s_and_b32 s23, s38, 0xfff
	s_add_i32 s40, s40, s9
	s_mulk_i32 s8, 0x1100
	s_add_u32 s8, s8, s23
	s_addc_u32 s9, s40, 0
	s_mul_i32 s23, s9, 0x500
	v_mad_u64_u32 v[30:31], s[8:9], s8, v42, v[36:37]
	v_add_u32_e32 v31, s23, v31
	v_cvt_pk_bf16_f32 v26, v2, v3
	v_cvt_pk_bf16_f32 v27, v4, v5
	v_cvt_pk_bf16_f32 v28, v10, v11
	v_cvt_pk_bf16_f32 v29, v12, v13
	global_store_dwordx4 v[30:31], v[26:29], off nt
	s_andn2_b64 vcc, exec, s[4:5]
	s_cbranch_vccz .LBB0_27

.LBB0_27:
	s_ashr_i64 s[4:5], s[42:43], 12
	s_mulk_i32 s5, 0x1100
	s_mul_hi_u32 s9, s4, 0x1100
	s_and_b32 s8, s42, 0xfff
	s_add_i32 s9, s9, s5
	s_mulk_i32 s4, 0x1100
	s_add_u32 s4, s4, s8
	s_addc_u32 s5, s9, 0
	s_mul_i32 s8, s5, 0x500
	v_mad_u64_u32 v[30:31], s[4:5], s4, v42, v[36:37]
	v_add_u32_e32 v31, s8, v31
	v_cvt_pk_bf16_f32 v26, v6, v7
	v_cvt_pk_bf16_f32 v27, v8, v9
	v_cvt_pk_bf16_f32 v28, v18, v19
	v_cvt_pk_bf16_f32 v29, v20, v21
	global_store_dwordx4 v[30:31], v[26:29], off nt
	s_andn2_b64 vcc, exec, s[6:7]
	s_cbranch_vccnz .LBB0_16
.LBB0_28:
	s_ashr_i64 s[4:5], s[44:45], 12
	s_mulk_i32 s5, 0x1100
	s_mul_hi_u32 s7, s4, 0x1100
	s_and_b32 s6, s44, 0xfff
	s_add_i32 s7, s7, s5
	s_mulk_i32 s4, 0x1100
	s_add_u32 s4, s4, s6
	s_addc_u32 s5, s7, 0
	s_mul_i32 s6, s5, 0x500
	v_mad_u64_u32 v[30:31], s[4:5], s4, v42, v[36:37]
	v_add_u32_e32 v31, s6, v31
	v_cvt_pk_bf16_f32 v26, v14, v15
	v_cvt_pk_bf16_f32 v27, v16, v17
	v_cvt_pk_bf16_f32 v28, v22, v23
	v_cvt_pk_bf16_f32 v29, v24, v25
	global_store_dwordx4 v[30:31], v[26:29], off nt
	s_branch .LBB0_16
